# static s_setprio 1 for waves 4-7 at GEMM phase heads with the per-segment flips kept
# speedup vs baseline: 1.0027x; 1.0001x over previous
.Lgprio_skip3:
	s_bitcmp1_b32 s2, 0
	s_cbranch_scc1 .Ldf_skip_p6
	v_writelane_b32 v234, s0, 0
	v_writelane_b32 v234, s1, 1
	v_writelane_b32 v234, s2, 2
	v_writelane_b32 v234, s3, 3
	v_writelane_b32 v234, s4, 4
	v_writelane_b32 v234, s5, 5
	v_writelane_b32 v234, s6, 6
	v_writelane_b32 v234, s7, 7
	v_writelane_b32 v234, s8, 8
	v_writelane_b32 v234, s9, 9
	v_writelane_b32 v234, s10, 10
	v_writelane_b32 v234, s11, 11
	v_writelane_b32 v234, s12, 12
	v_writelane_b32 v234, s13, 13
	v_writelane_b32 v234, s14, 14
	v_writelane_b32 v234, s15, 15
	v_writelane_b32 v234, s16, 16
	v_writelane_b32 v234, s17, 17
	v_writelane_b32 v234, s18, 18
	v_writelane_b32 v234, s19, 19
	v_writelane_b32 v234, s20, 20
	v_writelane_b32 v234, s21, 21
	v_writelane_b32 v234, s22, 22
	v_writelane_b32 v234, s23, 23
	v_writelane_b32 v234, s24, 24
	v_writelane_b32 v234, s25, 25
	v_writelane_b32 v234, s26, 26
	v_writelane_b32 v234, s27, 27
	v_writelane_b32 v234, s28, 28
	v_writelane_b32 v234, s29, 29
	v_writelane_b32 v234, s30, 30
	v_writelane_b32 v234, s31, 31
	v_writelane_b32 v234, s32, 32
	v_writelane_b32 v234, s33, 33
	v_writelane_b32 v234, s34, 34
	v_writelane_b32 v234, s35, 35
	v_writelane_b32 v234, s36, 36
	v_writelane_b32 v234, s37, 37
	v_writelane_b32 v234, s38, 38
	v_writelane_b32 v234, s39, 39
	v_writelane_b32 v234, s40, 40
	v_writelane_b32 v234, s41, 41
	v_writelane_b32 v234, s42, 42
	v_writelane_b32 v234, s43, 43
	v_writelane_b32 v234, s44, 44
	v_writelane_b32 v234, s45, 45
	v_writelane_b32 v234, s46, 46
	v_writelane_b32 v234, s47, 47
	v_writelane_b32 v234, s48, 48
	v_writelane_b32 v234, s49, 49
	v_writelane_b32 v234, s50, 50
	v_writelane_b32 v234, s51, 51
	v_writelane_b32 v234, s52, 52
	v_writelane_b32 v234, s53, 53
	v_writelane_b32 v234, s54, 54
	v_writelane_b32 v234, s55, 55
	v_writelane_b32 v234, s56, 56
	v_writelane_b32 v234, s57, 57
	v_writelane_b32 v234, s58, 58
	v_writelane_b32 v234, s59, 59
	v_writelane_b32 v234, s60, 60
	v_writelane_b32 v234, s61, 61
	v_writelane_b32 v234, s62, 62
	v_writelane_b32 v234, s63, 63
	v_writelane_b32 v235, s64, 0
	v_writelane_b32 v235, s65, 1
	v_writelane_b32 v235, s66, 2
	v_writelane_b32 v235, s67, 3
	v_writelane_b32 v235, s68, 4
	v_writelane_b32 v235, s69, 5
	v_writelane_b32 v235, s70, 6
	v_writelane_b32 v235, s71, 7
	v_writelane_b32 v235, s72, 8
	v_writelane_b32 v235, s73, 9
	v_writelane_b32 v235, s74, 10
	v_writelane_b32 v235, s75, 11
	v_writelane_b32 v235, s76, 12
	v_writelane_b32 v235, s77, 13
	v_writelane_b32 v235, s78, 14
	v_writelane_b32 v235, s79, 15
	v_writelane_b32 v235, s80, 16
	v_writelane_b32 v235, s81, 17
	v_writelane_b32 v235, s82, 18
	v_writelane_b32 v235, s83, 19
	v_writelane_b32 v235, s84, 20
	v_writelane_b32 v235, s85, 21
	v_writelane_b32 v235, s86, 22
	v_writelane_b32 v235, s87, 23
	v_writelane_b32 v235, s88, 24
	v_writelane_b32 v235, s89, 25
	v_writelane_b32 v235, s90, 26
	v_writelane_b32 v235, s91, 27
	v_writelane_b32 v235, s92, 28
	v_writelane_b32 v235, s93, 29
	v_writelane_b32 v235, s94, 30
	v_writelane_b32 v235, s95, 31
	v_writelane_b32 v235, s96, 32
	v_writelane_b32 v235, s97, 33
	v_writelane_b32 v235, vcc_lo, 34
	v_writelane_b32 v235, vcc_hi, 35
	v_readlane_b32 s70, v233, 45
	v_readlane_b32 s71, v233, 46
	s_add_u32 s22, s92, 0x4500000
	s_addc_u32 s23, s93, 0
	s_add_u32 s40, s92, 0x1400000
	s_addc_u32 s41, s93, 0
	v_mov_b32_e32 v0, v210
	s_nop 0
	v_readfirstlane_b32 s1, v0
	s_nop 3
	s_ashr_i32 s13, s1, 6
	s_lshr_b32 s0, s2, 1
	s_lshl_b32 s0, s0, 3
	s_add_i32 s33, s13, s0
	s_addk_i32 s33, 0x1c00
	s_movk_i32 s12, 0x80
	s_movk_i32 s101, 0x2400
	s_mov_b32 s100, 5
	s_branch .Lp3t_setup
